# v75: v56 + nt on the 16 P9 stores of the final f32 output (written once, never re-read on device; P9 overlaps P8's tail on other groups)
# baseline (speedup 1.0000x reference)
; #define LAS __attribute__((address_space(3)))
; __device__ __forceinline__ unsigned xb_add(unsigned* p, unsigned v) { return __hip_atomic_fetch_add(p, v, __ATOMIC_RELAXED, __HIP_MEMORY_SCOPE_AGENT); }
; __device__ __forceinline__ void p9_rows(LAS unsigned char* lds_, const Params& p) {
;     ...
;                 unsigned* qh = &bar[XB_Q9(v, F.wave)]; unsigned nx = 0u; if (F.lane == 0) nx = xb_add(qh, 1u);
;                 for (;;) {
;                     const int d = __builtin_amdgcn_readfirstlane((int)nx);
;                     if (d >= RPG / NWAVES) break;
;                     if (F.lane == 0) nx = xb_add(qh, 1u);
;                     const int r = v * RPG + d * NWAVES + F.wave;
;                     const float rstd1 = rsqrtf(wave_sum(ssq1[(size_t)r * 64 + F.lane]) * (1.0f / D) + EPS), rstd2 = rsqrtf(wave_sum(ssq2[(size_t)r * 64 + F.lane]) * (1.0f / D) + EPS);
;                     const float* xr = p.in[I_X] + (size_t)r * D; const bf16* mr = MIX + (size_t)r * D; const bf16* lr = MLP + (size_t)r * D; float* orow = p.out + (size_t)r * D;
; #pragma unroll
;                     for (int jg = 0; jg < 16; jg += 8) {
;                         f32x4 xv[8]; v2u m2[8], l2[8];
; #pragma unroll
;                         for (int j = 0; j < 8; ++j) { const int c = 256 * (jg + j) + 4 * F.lane; xv[j] = __builtin_nontemporal_load((const f32x4*)(xr + c)); m2[j] = __builtin_nontemporal_load((const v2u*)(mr + c)); l2[j] = __builtin_nontemporal_load((const v2u*)(lr + c)); }
; #pragma unroll
;                         for (int j = 0; j < 8; ++j) { const int c = 256 * (jg + j) + 4 * F.lane; const f32x4 a = *(LAS f32x4*)(cA + c), b = *(LAS f32x4*)(cB + c);
;                             const f32x4 mx = (f32x4){bf_lo(m2[j].x), bf_hi(m2[j].x), bf_lo(m2[j].y), bf_hi(m2[j].y)}, lx = (f32x4){bf_lo(l2[j].x), bf_hi(l2[j].x), bf_lo(l2[j].y), bf_hi(l2[j].y)};
.LBB0_1143:
	s_or_b64 exec, exec, s[4:5]
	s_lshl_b32 s4, s30, 3
	s_add_i32 s26, s44, s4
	s_ashr_i32 s27, s26, 31
	s_lshl_b64 s[4:5], s[26:27], 8
	v_lshl_or_b32 v0, v12, 2, s4
	v_mov_b32_e32 v1, s5
	v_lshl_add_u64 v[2:3], s[10:11], 0, v[0:1]
	v_lshl_add_u64 v[0:1], s[12:13], 0, v[0:1]
	global_load_dword v109, v[2:3], off
	global_load_dword v108, v[0:1], off
	s_lshl_b64 s[4:5], s[26:27], 14
	s_add_u32 s30, s64, s4
	s_addc_u32 s31, s65, s5
	s_lshl_b64 s[26:27], s[26:27], 13
	s_add_u32 s28, s8, s26
	s_addc_u32 s29, s9, s27
	v_lshlrev_b32_e32 v63, 1, v14
	global_load_dwordx2 v[110:111], v63, s[28:29] nt
	global_load_dwordx2 v[112:113], v63, s[28:29] offset:512 nt
	s_add_u32 s34, s6, s26
	s_addc_u32 s35, s7, s27
	global_load_dwordx2 v[114:115], v63, s[34:35] nt
	global_load_dwordx2 v[116:117], v63, s[34:35] offset:512 nt
	v_lshlrev_b32_e32 v140, 2, v14
	ds_read_b128 v[64:67], v19
	ds_read_b128 v[76:79], v19 offset:1024
	ds_read_b128 v[80:83], v19 offset:16384
	ds_read_b128 v[84:87], v19 offset:17408
	global_load_dwordx4 v[88:91], v140, s[30:31] nt
	global_load_dwordx4 v[92:95], v140, s[30:31] offset:1024 nt
	v_and_b32_e32 v0, 64, v29
	v_xor_b32_e32 v1, 1, v29
	v_add_u32_e32 v0, 64, v0
	v_xor_b32_e32 v2, 2, v29
	v_cmp_lt_i32_e32 vcc, v1, v0
	v_xor_b32_e32 v3, 4, v29
	v_xor_b32_e32 v4, 8, v29
	v_cndmask_b32_e32 v1, v29, v1, vcc
	v_cmp_lt_i32_e32 vcc, v2, v0
	v_xor_b32_e32 v5, 16, v29
	v_xor_b32_e32 v6, 32, v29
	v_cndmask_b32_e32 v2, v29, v2, vcc
	v_cmp_lt_i32_e32 vcc, v3, v0
	v_lshlrev_b32_e32 v70, 2, v1
	v_lshlrev_b32_e32 v136, 2, v2
	v_cndmask_b32_e32 v3, v29, v3, vcc
	v_cmp_lt_i32_e32 vcc, v4, v0
	v_lshlrev_b32_e32 v138, 2, v3
	v_readlane_b32 s68, v247, 5
	v_cndmask_b32_e32 v4, v29, v4, vcc
	v_cmp_lt_i32_e32 vcc, v5, v0
	v_lshlrev_b32_e32 v141, 2, v4
	v_readlane_b32 s82, v247, 19
	v_cndmask_b32_e32 v5, v29, v5, vcc
	v_cmp_lt_i32_e32 vcc, v6, v0
	v_lshlrev_b32_e32 v142, 2, v5
	v_readlane_b32 s83, v247, 20
	v_cndmask_b32_e32 v0, v29, v6, vcc
	v_lshlrev_b32_e32 v143, 2, v0
	global_load_dwordx4 v[96:99], v140, s[30:31] offset:2048 nt
	global_load_dwordx4 v[100:103], v140, s[30:31] offset:3072 nt
	global_load_dwordx4 v[104:107], v21, s[30:31] nt
	global_load_dwordx4 v[8:11], v23, s[30:31] nt
	global_load_dwordx4 v[4:7], v25, s[30:31] nt
	global_load_dwordx4 v[0:3], v27, s[30:31] nt
	global_load_dwordx2 v[118:119], v63, s[28:29] offset:1024 nt
	global_load_dwordx2 v[120:121], v63, s[28:29] offset:1536 nt
	global_load_dwordx2 v[122:123], v63, s[34:35] offset:1024 nt
	global_load_dwordx2 v[124:125], v63, s[28:29] offset:2048 nt
	global_load_dwordx2 v[126:127], v63, s[28:29] offset:2560 nt
	global_load_dwordx2 v[72:73], v63, s[28:29] offset:3072 nt
	global_load_dwordx2 v[68:69], v63, s[28:29] offset:3584 nt
	global_load_dwordx2 v[128:129], v63, s[34:35] offset:1536 nt
	s_mov_b64 s[26:27], s[82:83]
	s_add_u32 s26, s26, s4
	s_addc_u32 s27, s27, s5
	v_readlane_b32 s69, v247, 6
	v_readlane_b32 s70, v247, 7
	v_readlane_b32 s71, v247, 8
	v_readlane_b32 s72, v247, 9
	v_readlane_b32 s73, v247, 10
	v_readlane_b32 s74, v247, 11
	v_readlane_b32 s75, v247, 12
	v_readlane_b32 s76, v247, 13
	v_readlane_b32 s77, v247, 14
	v_readlane_b32 s78, v247, 15
	v_readlane_b32 s79, v247, 16
	v_readlane_b32 s80, v247, 17
	v_readlane_b32 s81, v247, 18
	s_waitcnt vmcnt(21)
	ds_bpermute_b32 v131, v70, v109
	s_waitcnt vmcnt(20)
	ds_bpermute_b32 v130, v70, v108
	global_load_dwordx2 v[132:133], v63, s[34:35] offset:2048 nt
	global_load_dwordx2 v[134:135], v63, s[34:35] offset:2560 nt
	global_load_dwordx2 v[74:75], v63, s[34:35] offset:3072 nt
	global_load_dwordx2 v[70:71], v63, s[34:35] offset:3584 nt
	s_waitcnt lgkmcnt(0)
	v_pk_add_f32 v[108:109], v[108:109], v[130:131]
	ds_bpermute_b32 v131, v136, v109
	ds_bpermute_b32 v130, v136, v108
	s_waitcnt vmcnt(23)
	v_lshlrev_b32_e32 v136, 16, v110
	v_and_b32_e32 v137, 0xffff0000, v110
	v_lshlrev_b32_e32 v110, 16, v111
	v_and_b32_e32 v111, 0xffff0000, v111
	s_waitcnt lgkmcnt(0)
	v_pk_add_f32 v[108:109], v[108:109], v[130:131]
	ds_bpermute_b32 v131, v138, v109
	ds_bpermute_b32 v130, v138, v108
	v_pk_mul_f32 v[136:137], v[64:65], v[136:137]
	v_pk_mul_f32 v[110:111], v[66:67], v[110:111]
	s_waitcnt vmcnt(22)
	v_lshlrev_b32_e32 v138, 16, v112
	v_and_b32_e32 v139, 0xffff0000, v112
	s_waitcnt lgkmcnt(0)
	v_pk_add_f32 v[108:109], v[108:109], v[130:131]
	ds_bpermute_b32 v131, v141, v109
	ds_bpermute_b32 v130, v141, v108
	v_lshlrev_b32_e32 v112, 16, v113
	v_and_b32_e32 v113, 0xffff0000, v113
	v_pk_mul_f32 v[112:113], v[78:79], v[112:113]
	v_pk_mul_f32 v[138:139], v[76:77], v[138:139]
	s_waitcnt lgkmcnt(0)
	v_pk_add_f32 v[64:65], v[108:109], v[130:131]
	ds_bpermute_b32 v67, v142, v65
	ds_bpermute_b32 v66, v142, v64
	s_waitcnt vmcnt(21)
	v_lshlrev_b32_e32 v76, 16, v114
	v_and_b32_e32 v77, 0xffff0000, v114
	v_lshlrev_b32_e32 v78, 16, v115
	v_and_b32_e32 v79, 0xffff0000, v115
	s_waitcnt lgkmcnt(0)
	v_pk_add_f32 v[64:65], v[64:65], v[66:67]
	ds_bpermute_b32 v67, v143, v65
	ds_bpermute_b32 v66, v143, v64
	v_pk_mul_f32 v[76:77], v[80:81], v[76:77]
	v_pk_mul_f32 v[78:79], v[82:83], v[78:79]
	s_waitcnt vmcnt(20)
	v_lshlrev_b32_e32 v108, 16, v116
	v_and_b32_e32 v109, 0xffff0000, v116
	s_waitcnt lgkmcnt(0)
	v_pk_add_f32 v[64:65], v[64:65], v[66:67]
	v_lshlrev_b32_e32 v114, 16, v117
	v_pk_fma_f32 v[64:65], v[64:65], s[18:19], v[62:63] op_sel_hi:[1,0,0]
	v_and_b32_e32 v115, 0xffff0000, v117
	v_mul_f32_e32 v63, 0x4b800000, v65
	v_cmp_gt_f32_e32 vcc, s43, v65
	v_mul_f32_e32 v66, 0x4b800000, v64
	v_cmp_gt_f32_e64 s[4:5], s43, v64
	v_cndmask_b32_e32 v63, v65, v63, vcc
	v_rsq_f32_e32 v63, v63
	v_cndmask_b32_e64 v64, v64, v66, s[4:5]
	v_rsq_f32_e32 v64, v64
	v_mul_f32_e32 v65, 0x45800000, v63
	v_cndmask_b32_e32 v66, v63, v65, vcc
	v_mul_f32_e32 v67, 0x45800000, v64
	v_cndmask_b32_e64 v64, v64, v67, s[4:5]
	s_waitcnt vmcnt(19)
; #define LAS __attribute__((address_space(3)))
; __device__ __forceinline__ void p9_rows(LAS unsigned char* lds_, const Params& p) {
;     ...
;                         for (int j = 0; j < 8; ++j) { const int c = 256 * (jg + j) + 4 * F.lane; xv[j] = __builtin_nontemporal_load((const f32x4*)(xr + c)); m2[j] = __builtin_nontemporal_load((const v2u*)(mr + c)); l2[j] = __builtin_nontemporal_load((const v2u*)(lr + c)); }
; #pragma unroll
;                         for (int j = 0; j < 8; ++j) { const int c = 256 * (jg + j) + 4 * F.lane; const f32x4 a = *(LAS f32x4*)(cA + c), b = *(LAS f32x4*)(cB + c);
;                             const f32x4 mx = (f32x4){bf_lo(m2[j].x), bf_hi(m2[j].x), bf_lo(m2[j].y), bf_hi(m2[j].y)}, lx = (f32x4){bf_lo(l2[j].x), bf_hi(l2[j].x), bf_lo(l2[j].y), bf_hi(l2[j].y)};
;                             const f32x4 x1 = xv[j] + a * mx * rstd1;
;                             *(f32x4*)(orow + c) = x1 + b * lx * rstd2; }
	v_pk_fma_f32 v[80:81], v[66:67], v[136:137], v[88:89] op_sel_hi:[0,1,1]
	v_pk_fma_f32 v[82:83], v[66:67], v[110:111], v[90:91] op_sel_hi:[0,1,1]
	v_pk_fma_f32 v[78:79], v[64:65], v[78:79], v[82:83] op_sel_hi:[0,1,1]
	v_pk_fma_f32 v[76:77], v[64:65], v[76:77], v[80:81] op_sel_hi:[0,1,1]
	global_store_dwordx4 v140, v[76:79], s[26:27] nt
	v_pk_mul_f32 v[80:81], v[84:85], v[108:109]
	v_pk_mul_f32 v[82:83], v[86:87], v[114:115]
	s_waitcnt vmcnt(19)
	v_pk_fma_f32 v[76:77], v[66:67], v[138:139], v[92:93] op_sel_hi:[0,1,1]
	v_pk_fma_f32 v[78:79], v[66:67], v[112:113], v[94:95] op_sel_hi:[0,1,1]
	v_pk_fma_f32 v[78:79], v[64:65], v[82:83], v[78:79] op_sel_hi:[0,1,1]
	v_pk_fma_f32 v[76:77], v[64:65], v[80:81], v[76:77] op_sel_hi:[0,1,1]
	global_store_dwordx4 v140, v[76:79], s[26:27] offset:1024 nt
	ds_read_b128 v[76:79], v19 offset:2048
	ds_read_b128 v[80:83], v19 offset:18432
	s_waitcnt vmcnt(13)
	v_lshlrev_b32_e32 v88, 16, v118
	v_and_b32_e32 v89, 0xffff0000, v118
	v_lshlrev_b32_e32 v90, 16, v119
	v_and_b32_e32 v91, 0xffff0000, v119
	ds_read_b128 v[84:87], v19 offset:3072
	s_waitcnt lgkmcnt(2)
	v_pk_mul_f32 v[78:79], v[78:79], v[90:91]
	v_pk_mul_f32 v[76:77], v[76:77], v[88:89]
	s_waitcnt vmcnt(11)
	v_lshlrev_b32_e32 v92, 16, v122
	v_and_b32_e32 v93, 0xffff0000, v122
	v_lshlrev_b32_e32 v94, 16, v123
	v_and_b32_e32 v95, 0xffff0000, v123
	v_pk_fma_f32 v[88:89], v[66:67], v[76:77], v[96:97] op_sel_hi:[0,1,1]
	v_pk_fma_f32 v[90:91], v[66:67], v[78:79], v[98:99] op_sel_hi:[0,1,1]
	ds_read_b128 v[76:79], v19 offset:19456
	s_waitcnt lgkmcnt(2)
	v_pk_mul_f32 v[80:81], v[80:81], v[92:93]
	v_pk_mul_f32 v[82:83], v[82:83], v[94:95]
	v_pk_fma_f32 v[80:81], v[64:65], v[80:81], v[88:89] op_sel_hi:[0,1,1]
	v_pk_fma_f32 v[82:83], v[64:65], v[82:83], v[90:91] op_sel_hi:[0,1,1]
	global_store_dwordx4 v140, v[80:83], s[26:27] offset:2048 nt
	s_waitcnt vmcnt(7)
	v_lshlrev_b32_e32 v88, 16, v128
	v_and_b32_e32 v89, 0xffff0000, v128
	v_lshlrev_b32_e32 v80, 16, v120
	v_and_b32_e32 v81, 0xffff0000, v120
	v_lshlrev_b32_e32 v82, 16, v121
	v_and_b32_e32 v83, 0xffff0000, v121
	v_lshlrev_b32_e32 v90, 16, v129
	v_and_b32_e32 v91, 0xffff0000, v129
	s_waitcnt lgkmcnt(1)
	v_pk_mul_f32 v[82:83], v[86:87], v[82:83]
	v_pk_mul_f32 v[80:81], v[84:85], v[80:81]
	v_pk_fma_f32 v[82:83], v[66:67], v[82:83], v[102:103] op_sel_hi:[0,1,1]
	v_pk_fma_f32 v[80:81], v[66:67], v[80:81], v[100:101] op_sel_hi:[0,1,1]
	s_waitcnt lgkmcnt(0)
	v_pk_mul_f32 v[76:77], v[76:77], v[88:89]
	v_pk_mul_f32 v[78:79], v[78:79], v[90:91]
	v_pk_fma_f32 v[76:77], v[64:65], v[76:77], v[80:81] op_sel_hi:[0,1,1]
	v_pk_fma_f32 v[78:79], v[64:65], v[78:79], v[82:83] op_sel_hi:[0,1,1]
	global_store_dwordx4 v140, v[76:79], s[26:27] offset:3072 nt
	ds_read_b128 v[76:79], v19 offset:4096
	ds_read_b128 v[80:83], v19 offset:20480
	v_lshlrev_b32_e32 v88, 16, v124
	v_and_b32_e32 v89, 0xffff0000, v124
	v_lshlrev_b32_e32 v90, 16, v125
	v_and_b32_e32 v91, 0xffff0000, v125
	ds_read_b128 v[84:87], v19 offset:5120
	s_waitcnt lgkmcnt(2)
	v_pk_mul_f32 v[78:79], v[78:79], v[90:91]
	v_pk_mul_f32 v[76:77], v[76:77], v[88:89]
	s_waitcnt vmcnt(7)
	v_lshlrev_b32_e32 v92, 16, v132
	v_and_b32_e32 v93, 0xffff0000, v132
	v_lshlrev_b32_e32 v94, 16, v133
	v_and_b32_e32 v95, 0xffff0000, v133
	v_pk_fma_f32 v[88:89], v[66:67], v[76:77], v[104:105] op_sel_hi:[0,1,1]
	v_pk_fma_f32 v[90:91], v[66:67], v[78:79], v[106:107] op_sel_hi:[0,1,1]
	ds_read_b128 v[76:79], v19 offset:21504
	s_waitcnt lgkmcnt(2)
	v_pk_mul_f32 v[80:81], v[80:81], v[92:93]
	v_pk_mul_f32 v[82:83], v[82:83], v[94:95]
	v_pk_fma_f32 v[80:81], v[64:65], v[80:81], v[88:89] op_sel_hi:[0,1,1]
	v_pk_fma_f32 v[82:83], v[64:65], v[82:83], v[90:91] op_sel_hi:[0,1,1]
	global_store_dwordx4 v21, v[80:83], s[26:27] nt
	s_waitcnt vmcnt(7)
	v_lshlrev_b32_e32 v88, 16, v134
	v_and_b32_e32 v89, 0xffff0000, v134
	v_lshlrev_b32_e32 v80, 16, v126
	v_and_b32_e32 v81, 0xffff0000, v126
	v_lshlrev_b32_e32 v82, 16, v127
	v_and_b32_e32 v83, 0xffff0000, v127
	v_lshlrev_b32_e32 v90, 16, v135
	v_and_b32_e32 v91, 0xffff0000, v135
	s_waitcnt lgkmcnt(1)
	v_pk_mul_f32 v[82:83], v[86:87], v[82:83]
	v_pk_mul_f32 v[80:81], v[84:85], v[80:81]
	v_pk_fma_f32 v[10:11], v[66:67], v[82:83], v[10:11] op_sel_hi:[0,1,1]
	v_pk_fma_f32 v[8:9], v[66:67], v[80:81], v[8:9] op_sel_hi:[0,1,1]
	s_waitcnt lgkmcnt(0)
	v_pk_mul_f32 v[76:77], v[76:77], v[88:89]
	v_pk_mul_f32 v[78:79], v[78:79], v[90:91]
	v_pk_fma_f32 v[8:9], v[64:65], v[76:77], v[8:9] op_sel_hi:[0,1,1]
	v_pk_fma_f32 v[10:11], v[64:65], v[78:79], v[10:11] op_sel_hi:[0,1,1]
	global_store_dwordx4 v23, v[8:11], s[26:27] nt
	ds_read_b128 v[8:11], v19 offset:6144
	ds_read_b128 v[76:79], v19 offset:22528
	v_lshlrev_b32_e32 v80, 16, v72
	v_and_b32_e32 v81, 0xffff0000, v72
	v_lshlrev_b32_e32 v82, 16, v73
	v_and_b32_e32 v83, 0xffff0000, v73
	s_waitcnt vmcnt(7)
	v_lshlrev_b32_e32 v84, 16, v74
	v_and_b32_e32 v85, 0xffff0000, v74
	v_lshlrev_b32_e32 v86, 16, v75
	v_and_b32_e32 v87, 0xffff0000, v75
	ds_read_b128 v[72:75], v19 offset:7168
	s_waitcnt lgkmcnt(2)
	v_pk_mul_f32 v[10:11], v[10:11], v[82:83]
	v_pk_mul_f32 v[8:9], v[8:9], v[80:81]
	v_pk_fma_f32 v[10:11], v[66:67], v[10:11], v[6:7] op_sel_hi:[0,1,1]
	v_pk_fma_f32 v[8:9], v[66:67], v[8:9], v[4:5] op_sel_hi:[0,1,1]
	ds_read_b128 v[4:7], v19 offset:23552
	s_waitcnt lgkmcnt(2)
	v_pk_mul_f32 v[76:77], v[76:77], v[84:85]
	v_pk_mul_f32 v[78:79], v[78:79], v[86:87]
	v_pk_fma_f32 v[8:9], v[64:65], v[76:77], v[8:9] op_sel_hi:[0,1,1]
	v_pk_fma_f32 v[10:11], v[64:65], v[78:79], v[10:11] op_sel_hi:[0,1,1]
	global_store_dwordx4 v25, v[8:11], s[26:27] nt
	v_lshlrev_b32_e32 v63, 2, v16
	v_lshlrev_b32_e32 v136, 2, v22
	v_lshlrev_b32_e32 v8, 16, v68
	v_and_b32_e32 v9, 0xffff0000, v68
	v_lshlrev_b32_e32 v10, 16, v69
	v_and_b32_e32 v11, 0xffff0000, v69
	s_waitcnt vmcnt(7)
; #define LAS __attribute__((address_space(3)))
; __device__ __forceinline__ void p9_rows(LAS unsigned char* lds_, const Params& p) {
;     ...
;                     for (int jg = 0; jg < 16; jg += 8) {
;                         f32x4 xv[8]; v2u m2[8], l2[8];
; #pragma unroll
;                         for (int j = 0; j < 8; ++j) { const int c = 256 * (jg + j) + 4 * F.lane; xv[j] = __builtin_nontemporal_load((const f32x4*)(xr + c)); m2[j] = __builtin_nontemporal_load((const v2u*)(mr + c)); l2[j] = __builtin_nontemporal_load((const v2u*)(lr + c)); }
; #pragma unroll
;                         for (int j = 0; j < 8; ++j) { const int c = 256 * (jg + j) + 4 * F.lane; const f32x4 a = *(LAS f32x4*)(cA + c), b = *(LAS f32x4*)(cB + c);
;                             const f32x4 mx = (f32x4){bf_lo(m2[j].x), bf_hi(m2[j].x), bf_lo(m2[j].y), bf_hi(m2[j].y)}, lx = (f32x4){bf_lo(l2[j].x), bf_hi(l2[j].x), bf_lo(l2[j].y), bf_hi(l2[j].y)};
;                             const f32x4 x1 = xv[j] + a * mx * rstd1;
;                             *(f32x4*)(orow + c) = x1 + b * lx * rstd2; }
	v_lshlrev_b32_e32 v68, 16, v70
	v_and_b32_e32 v69, 0xffff0000, v70
	v_lshlrev_b32_e32 v70, 16, v71
	v_and_b32_e32 v71, 0xffff0000, v71
	s_waitcnt lgkmcnt(1)
	v_pk_mul_f32 v[8:9], v[72:73], v[8:9]
	v_pk_mul_f32 v[10:11], v[74:75], v[10:11]
	v_pk_fma_f32 v[0:1], v[66:67], v[8:9], v[0:1] op_sel_hi:[0,1,1]
	v_pk_fma_f32 v[2:3], v[66:67], v[10:11], v[2:3] op_sel_hi:[0,1,1]
	s_waitcnt lgkmcnt(0)
	v_pk_mul_f32 v[6:7], v[6:7], v[70:71]
	v_pk_mul_f32 v[4:5], v[4:5], v[68:69]
	v_pk_fma_f32 v[2:3], v[64:65], v[6:7], v[2:3] op_sel_hi:[0,1,1]
	v_pk_fma_f32 v[0:1], v[64:65], v[4:5], v[0:1] op_sel_hi:[0,1,1]
	global_store_dwordx4 v27, v[0:3], s[26:27] nt
	v_lshlrev_b32_e32 v65, 2, v18
	v_lshlrev_b32_e32 v67, 2, v20
	v_lshlrev_b32_e32 v0, 1, v16
	global_load_dwordx2 v[104:105], v0, s[28:29] nt
	global_load_dwordx2 v[106:107], v0, s[34:35] nt
	global_load_dwordx4 v[72:75], v63, s[30:31] nt
	v_lshlrev_b32_e32 v0, 1, v18
	global_load_dwordx2 v[108:109], v0, s[28:29] nt
	global_load_dwordx2 v[110:111], v0, s[34:35] nt
	global_load_dwordx4 v[76:79], v65, s[30:31] nt
	v_lshlrev_b32_e32 v0, 1, v20
	global_load_dwordx2 v[112:113], v0, s[28:29] nt
	global_load_dwordx2 v[114:115], v0, s[34:35] nt
	global_load_dwordx4 v[80:83], v67, s[30:31] nt
	global_load_dwordx4 v[84:87], v136, s[30:31] nt
	v_lshlrev_b32_e32 v0, 1, v22
	global_load_dwordx2 v[116:117], v0, s[28:29] nt
	global_load_dwordx2 v[118:119], v0, s[34:35] nt
	v_lshlrev_b32_e32 v137, 2, v24
	v_lshlrev_b32_e32 v0, 1, v24
	global_load_dwordx4 v[88:91], v137, s[30:31] nt
	global_load_dwordx2 v[120:121], v0, s[28:29] nt
	global_load_dwordx2 v[122:123], v0, s[34:35] nt
	v_lshlrev_b32_e32 v138, 2, v26
	v_lshlrev_b32_e32 v0, 1, v26
	global_load_dwordx4 v[92:95], v138, s[30:31] nt
	global_load_dwordx2 v[124:125], v0, s[28:29] nt
	global_load_dwordx2 v[126:127], v0, s[34:35] nt
	v_lshlrev_b32_e32 v139, 2, v28
	v_lshlrev_b32_e32 v0, 1, v28
	global_load_dwordx4 v[4:7], v139, s[30:31] nt
	global_load_dwordx2 v[70:71], v0, s[28:29] nt
	global_load_dwordx2 v[68:69], v0, s[34:35] nt
	v_lshlrev_b32_e32 v140, 2, v30
	v_lshlrev_b32_e32 v96, 1, v30
	global_load_dwordx4 v[0:3], v140, s[30:31] nt
	global_load_dwordx2 v[10:11], v96, s[28:29] nt
	global_load_dwordx2 v[8:9], v96, s[34:35] nt
	ds_read_b128 v[96:99], v19 offset:8192
	ds_read_b128 v[100:103], v19 offset:24576
	s_waitcnt vmcnt(23)
	v_lshlrev_b32_e32 v128, 16, v104
	v_and_b32_e32 v129, 0xffff0000, v104
	v_lshlrev_b32_e32 v130, 16, v105
	v_and_b32_e32 v131, 0xffff0000, v105
	s_waitcnt vmcnt(22)
	v_lshlrev_b32_e32 v132, 16, v106
	v_and_b32_e32 v133, 0xffff0000, v106
	v_lshlrev_b32_e32 v134, 16, v107
	v_and_b32_e32 v135, 0xffff0000, v107
	ds_read_b128 v[104:107], v19 offset:9216
	s_waitcnt lgkmcnt(2)
	v_pk_mul_f32 v[98:99], v[98:99], v[130:131]
	v_pk_mul_f32 v[96:97], v[96:97], v[128:129]
	s_waitcnt vmcnt(21)
	v_pk_fma_f32 v[98:99], v[66:67], v[98:99], v[74:75] op_sel_hi:[0,1,1]
	v_pk_fma_f32 v[96:97], v[66:67], v[96:97], v[72:73] op_sel_hi:[0,1,1]
	ds_read_b128 v[72:75], v19 offset:25600
	s_waitcnt lgkmcnt(2)
	v_pk_mul_f32 v[100:101], v[100:101], v[132:133]
	v_pk_mul_f32 v[102:103], v[102:103], v[134:135]
	v_pk_fma_f32 v[96:97], v[64:65], v[100:101], v[96:97] op_sel_hi:[0,1,1]
	v_pk_fma_f32 v[98:99], v[64:65], v[102:103], v[98:99] op_sel_hi:[0,1,1]
	global_store_dwordx4 v63, v[96:99], s[26:27] nt
	s_waitcnt vmcnt(20)
	v_lshlrev_b32_e32 v100, 16, v110
	v_and_b32_e32 v101, 0xffff0000, v110
	v_lshlrev_b32_e32 v96, 16, v108
	v_and_b32_e32 v97, 0xffff0000, v108
	v_lshlrev_b32_e32 v98, 16, v109
	v_and_b32_e32 v99, 0xffff0000, v109
	v_lshlrev_b32_e32 v102, 16, v111
	v_and_b32_e32 v103, 0xffff0000, v111
	s_waitcnt lgkmcnt(1)
	v_pk_mul_f32 v[98:99], v[106:107], v[98:99]
	v_pk_mul_f32 v[96:97], v[104:105], v[96:97]
	s_waitcnt vmcnt(19)
	v_pk_fma_f32 v[78:79], v[66:67], v[98:99], v[78:79] op_sel_hi:[0,1,1]
	v_pk_fma_f32 v[76:77], v[66:67], v[96:97], v[76:77] op_sel_hi:[0,1,1]
	s_waitcnt lgkmcnt(0)
	v_pk_mul_f32 v[72:73], v[72:73], v[100:101]
	v_pk_mul_f32 v[74:75], v[74:75], v[102:103]
	v_pk_fma_f32 v[72:73], v[64:65], v[72:73], v[76:77] op_sel_hi:[0,1,1]
	v_pk_fma_f32 v[74:75], v[64:65], v[74:75], v[78:79] op_sel_hi:[0,1,1]
	global_store_dwordx4 v65, v[72:75], s[26:27] nt
	ds_read_b128 v[72:75], v19 offset:10240
	ds_read_b128 v[76:79], v19 offset:26624
	s_waitcnt vmcnt(19)
	v_lshlrev_b32_e32 v100, 16, v112
	v_and_b32_e32 v101, 0xffff0000, v112
	v_lshlrev_b32_e32 v102, 16, v113
	v_and_b32_e32 v103, 0xffff0000, v113
	ds_read_b128 v[96:99], v19 offset:11264
	s_waitcnt lgkmcnt(2)
	v_pk_mul_f32 v[74:75], v[74:75], v[102:103]
	v_pk_mul_f32 v[72:73], v[72:73], v[100:101]
	s_waitcnt vmcnt(18)
	v_lshlrev_b32_e32 v104, 16, v114
	v_and_b32_e32 v105, 0xffff0000, v114
	v_lshlrev_b32_e32 v106, 16, v115
	v_and_b32_e32 v107, 0xffff0000, v115
	s_waitcnt vmcnt(17)
	v_pk_fma_f32 v[80:81], v[66:67], v[72:73], v[80:81] op_sel_hi:[0,1,1]
	v_pk_fma_f32 v[82:83], v[66:67], v[74:75], v[82:83] op_sel_hi:[0,1,1]
	ds_read_b128 v[72:75], v19 offset:27648
	s_waitcnt lgkmcnt(2)
; #define LAS __attribute__((address_space(3)))
; __device__ __forceinline__ void p9_rows(LAS unsigned char* lds_, const Params& p) {
;     ...
;                     for (int jg = 0; jg < 16; jg += 8) {
;                         f32x4 xv[8]; v2u m2[8], l2[8];
; #pragma unroll
;                         for (int j = 0; j < 8; ++j) { const int c = 256 * (jg + j) + 4 * F.lane; xv[j] = __builtin_nontemporal_load((const f32x4*)(xr + c)); m2[j] = __builtin_nontemporal_load((const v2u*)(mr + c)); l2[j] = __builtin_nontemporal_load((const v2u*)(lr + c)); }
; #pragma unroll
;                         for (int j = 0; j < 8; ++j) { const int c = 256 * (jg + j) + 4 * F.lane; const f32x4 a = *(LAS f32x4*)(cA + c), b = *(LAS f32x4*)(cB + c);
;                             const f32x4 mx = (f32x4){bf_lo(m2[j].x), bf_hi(m2[j].x), bf_lo(m2[j].y), bf_hi(m2[j].y)}, lx = (f32x4){bf_lo(l2[j].x), bf_hi(l2[j].x), bf_lo(l2[j].y), bf_hi(l2[j].y)};
;                             const f32x4 x1 = xv[j] + a * mx * rstd1;
;                             *(f32x4*)(orow + c) = x1 + b * lx * rstd2; }
	v_pk_mul_f32 v[76:77], v[76:77], v[104:105]
	v_pk_mul_f32 v[78:79], v[78:79], v[106:107]
	v_pk_fma_f32 v[76:77], v[64:65], v[76:77], v[80:81] op_sel_hi:[0,1,1]
	v_pk_fma_f32 v[78:79], v[64:65], v[78:79], v[82:83] op_sel_hi:[0,1,1]
	global_store_dwordx4 v67, v[76:79], s[26:27] nt
	s_waitcnt vmcnt(15)
	v_lshlrev_b32_e32 v80, 16, v118
	v_and_b32_e32 v81, 0xffff0000, v118
	v_lshlrev_b32_e32 v76, 16, v116
	v_and_b32_e32 v77, 0xffff0000, v116
	v_lshlrev_b32_e32 v78, 16, v117
	v_and_b32_e32 v79, 0xffff0000, v117
	v_lshlrev_b32_e32 v82, 16, v119
	v_and_b32_e32 v83, 0xffff0000, v119
	s_waitcnt lgkmcnt(1)
	v_pk_mul_f32 v[78:79], v[98:99], v[78:79]
	v_pk_mul_f32 v[76:77], v[96:97], v[76:77]
	v_pk_fma_f32 v[78:79], v[66:67], v[78:79], v[86:87] op_sel_hi:[0,1,1]
	v_pk_fma_f32 v[76:77], v[66:67], v[76:77], v[84:85] op_sel_hi:[0,1,1]
	s_waitcnt lgkmcnt(0)
	v_pk_mul_f32 v[72:73], v[72:73], v[80:81]
	v_pk_mul_f32 v[74:75], v[74:75], v[82:83]
	v_pk_fma_f32 v[72:73], v[64:65], v[72:73], v[76:77] op_sel_hi:[0,1,1]
	v_pk_fma_f32 v[74:75], v[64:65], v[74:75], v[78:79] op_sel_hi:[0,1,1]
	global_store_dwordx4 v136, v[72:75], s[26:27] nt
	ds_read_b128 v[72:75], v19 offset:12288
	ds_read_b128 v[76:79], v19 offset:28672
	s_waitcnt vmcnt(14)
	v_lshlrev_b32_e32 v84, 16, v120
	v_and_b32_e32 v85, 0xffff0000, v120
	v_lshlrev_b32_e32 v86, 16, v121
	v_and_b32_e32 v87, 0xffff0000, v121
	ds_read_b128 v[80:83], v19 offset:13312
	s_waitcnt lgkmcnt(2)
	v_pk_mul_f32 v[74:75], v[74:75], v[86:87]
	v_pk_mul_f32 v[72:73], v[72:73], v[84:85]
	s_waitcnt vmcnt(13)
	v_lshlrev_b32_e32 v96, 16, v122
	v_and_b32_e32 v97, 0xffff0000, v122
	v_lshlrev_b32_e32 v98, 16, v123
	v_and_b32_e32 v99, 0xffff0000, v123
	v_pk_fma_f32 v[84:85], v[66:67], v[72:73], v[88:89] op_sel_hi:[0,1,1]
	v_pk_fma_f32 v[86:87], v[66:67], v[74:75], v[90:91] op_sel_hi:[0,1,1]
	ds_read_b128 v[72:75], v19 offset:29696
	s_waitcnt lgkmcnt(2)
	v_pk_mul_f32 v[76:77], v[76:77], v[96:97]
	v_pk_mul_f32 v[78:79], v[78:79], v[98:99]
	v_pk_fma_f32 v[76:77], v[64:65], v[76:77], v[84:85] op_sel_hi:[0,1,1]
	v_pk_fma_f32 v[78:79], v[64:65], v[78:79], v[86:87] op_sel_hi:[0,1,1]
	global_store_dwordx4 v137, v[76:79], s[26:27] nt
	s_waitcnt vmcnt(11)
	v_lshlrev_b32_e32 v84, 16, v126
	v_and_b32_e32 v85, 0xffff0000, v126
	v_lshlrev_b32_e32 v76, 16, v124
	v_and_b32_e32 v77, 0xffff0000, v124
	v_lshlrev_b32_e32 v78, 16, v125
	v_and_b32_e32 v79, 0xffff0000, v125
	v_lshlrev_b32_e32 v86, 16, v127
	v_and_b32_e32 v87, 0xffff0000, v127
	s_waitcnt lgkmcnt(1)
	v_pk_mul_f32 v[78:79], v[82:83], v[78:79]
	v_pk_mul_f32 v[76:77], v[80:81], v[76:77]
	v_pk_fma_f32 v[78:79], v[66:67], v[78:79], v[94:95] op_sel_hi:[0,1,1]
	v_pk_fma_f32 v[76:77], v[66:67], v[76:77], v[92:93] op_sel_hi:[0,1,1]
	s_waitcnt lgkmcnt(0)
	v_pk_mul_f32 v[72:73], v[72:73], v[84:85]
	v_pk_mul_f32 v[74:75], v[74:75], v[86:87]
	v_pk_fma_f32 v[72:73], v[64:65], v[72:73], v[76:77] op_sel_hi:[0,1,1]
	v_pk_fma_f32 v[74:75], v[64:65], v[74:75], v[78:79] op_sel_hi:[0,1,1]
	global_store_dwordx4 v138, v[72:75], s[26:27] nt
	ds_read_b128 v[72:75], v19 offset:14336
	ds_read_b128 v[76:79], v19 offset:30720
	s_waitcnt vmcnt(10)
	v_lshlrev_b32_e32 v80, 16, v70
	v_and_b32_e32 v81, 0xffff0000, v70
	v_lshlrev_b32_e32 v82, 16, v71
	v_and_b32_e32 v83, 0xffff0000, v71
	s_waitcnt vmcnt(9)
	v_lshlrev_b32_e32 v84, 16, v68
	v_and_b32_e32 v85, 0xffff0000, v68
	v_lshlrev_b32_e32 v86, 16, v69
	v_and_b32_e32 v87, 0xffff0000, v69
	ds_read_b128 v[68:71], v19 offset:15360
	s_waitcnt lgkmcnt(2)
	v_pk_mul_f32 v[74:75], v[74:75], v[82:83]
	v_pk_mul_f32 v[72:73], v[72:73], v[80:81]
	v_pk_fma_f32 v[74:75], v[66:67], v[74:75], v[6:7] op_sel_hi:[0,1,1]
	v_pk_fma_f32 v[72:73], v[66:67], v[72:73], v[4:5] op_sel_hi:[0,1,1]
	ds_read_b128 v[4:7], v19 offset:31744
	s_waitcnt lgkmcnt(2)
	v_pk_mul_f32 v[76:77], v[76:77], v[84:85]
	v_pk_mul_f32 v[78:79], v[78:79], v[86:87]
	v_pk_fma_f32 v[72:73], v[64:65], v[76:77], v[72:73] op_sel_hi:[0,1,1]
	v_pk_fma_f32 v[74:75], v[64:65], v[78:79], v[74:75] op_sel_hi:[0,1,1]
	global_store_dwordx4 v139, v[72:75], s[26:27] nt
	s_waitcnt vmcnt(8)
	s_nop 0
	v_lshlrev_b32_e32 v72, 16, v10
	v_and_b32_e32 v73, 0xffff0000, v10
	v_lshlrev_b32_e32 v10, 16, v11
	v_and_b32_e32 v11, 0xffff0000, v11
	s_waitcnt vmcnt(7)
	v_lshlrev_b32_e32 v74, 16, v8
	v_and_b32_e32 v75, 0xffff0000, v8
	v_lshlrev_b32_e32 v8, 16, v9
	v_and_b32_e32 v9, 0xffff0000, v9
	s_waitcnt lgkmcnt(1)
	v_pk_mul_f32 v[68:69], v[68:69], v[72:73]
	v_pk_mul_f32 v[10:11], v[70:71], v[10:11]
	v_pk_fma_f32 v[0:1], v[66:67], v[68:69], v[0:1] op_sel_hi:[0,1,1]
	v_pk_fma_f32 v[2:3], v[66:67], v[10:11], v[2:3] op_sel_hi:[0,1,1]
	s_waitcnt lgkmcnt(0)
	v_pk_mul_f32 v[6:7], v[6:7], v[8:9]
	v_pk_mul_f32 v[4:5], v[4:5], v[74:75]
	v_pk_fma_f32 v[2:3], v[64:65], v[6:7], v[2:3] op_sel_hi:[0,1,1]
	v_pk_fma_f32 v[0:1], v[64:65], v[4:5], v[0:1] op_sel_hi:[0,1,1]
	global_store_dwordx4 v140, v[0:3], s[26:27] nt
